# reuse across phases through d_ws: r1 publishes each item's cum tile, r3 reloads it instead of recomputing build_cum
# speedup vs baseline: 1.0009x; 1.0009x over previous
; #define LAS __attribute__((address_space(3)))
; __device__ __forceinline__ int otid() { int t = threadIdx.x; asm volatile("" : "+v"(t)); return t; }
; __device__ __forceinline__ void r3_item(const Args& a, int L, int item, LAS unsigned char* lds) {
;     const int tid = otid(), wid = tid >> 6, lane = tid & 63, r32 = lane & 31, hi = lane >> 5;
;     const int b = item >> 9, hl = (item >> 6) & 7, c = item & 63; const long R0 = (long)b * T + c * 64;
;     const bf16_t* proj = (const bf16_t*)(a.ws + WS_PROJ);
;     __syncthreads();
;     build_cum(a, L, hl, R0, proj, lds);
.LBB0_117:
	s_bfe_u32 s28, s15, 0x30006
	s_cmp_lt_u32 s28, 4
	v_mov_b32_e32 v24, v206
	v_mov_b32_e32 v20, v206
	s_cselect_b64 s[2:3], -1, 0
	s_cmp_gt_u32 s28, 3
	s_waitcnt lgkmcnt(0)
	s_barrier
	s_cselect_b64 s[6:7], -1, 0
	s_ashr_i32 s4, s15, 9
	s_ashr_i32 s5, s4, 31
	v_lshlrev_b32_e32 v0, 6, v24
	s_lshl_b32 s0, s15, 15
	s_add_u32 s0, s98, s0
	s_addc_u32 s1, s99, 0
	s_add_u32 s0, s0, 0x24300000
	s_addc_u32 s1, s1, 0
	global_load_dwordx4 v[52:55], v0, s[0:1]
	global_load_dwordx4 v[56:59], v0, s[0:1] offset:16
	global_load_dwordx4 v[60:63], v0, s[0:1] offset:32
	global_load_dwordx4 v[64:67], v0, s[0:1] offset:48
	s_waitcnt vmcnt(0)
	ds_write_b128 v0, v[52:55]
	ds_write_b128 v0, v[56:59] offset:16
	ds_write_b128 v0, v[60:63] offset:32
	ds_write_b128 v0, v[64:67] offset:48
	s_mov_b64 s[0:1], exec

; #define LAS __attribute__((address_space(3)))
; __device__ __forceinline__ unsigned f2bf(float f) { unsigned u = __builtin_bit_cast(unsigned, f); return (u + 0x7fffu + ((u >> 16) & 1u)) >> 16; }
; __device__ __forceinline__ void r1_item(const Args& a, int L, int item, LAS unsigned char* lds) {
;     ...
;     __syncthreads();
;     build_cum(a, L, hl, R0, proj, lds);
;     LAS float* cum = (LAS float*)(lds + L_CUM);
;     LAS bf16_t* VT = (LAS bf16_t*)(lds + L_VT); LAS bf16_t* KeT = (LAS bf16_t*)(lds + L_QK);
;     if (tid < 256) { const int i = (tid >> 2) & 63, g = tid & 3; const int kcol = hl < 4 ? GK + hl * 64 : RK + (hl - 4) * 64;
;         float va[8], vb[8]; load_qk16(a, proj + (R0 + i) * LD + kcol, hl, c * 64 + i, g, va, vb);
; #pragma unroll
;         for (int dir = 0; dir < 2; ++dir) { const int lastrow = dir == 0 ? 63 : 64;
; #pragma unroll
;             for (int e = 0; e < 8; ++e) { const int ka = g * 8 + e, kb = 32 + g * 8 + e;
;                 const float wa = __expf(cum[lastrow * 64 + ka] - cum[(dir * 64 + i) * 64 + ka]), wb = __expf(cum[lastrow * 64 + kb] - cum[(dir * 64 + i) * 64 + kb]);
;                 KeT[(dir * 64 + ka) * PT + i] = (bf16_t)f2bf(va[e] * wa); KeT[(dir * 64 + kb) * PT + i] = (bf16_t)f2bf(vb[e] * wb); } }
;     } else { const int t2 = tid - 256, j = t2 >> 2, vg = t2 & 3; const int vcol = hl < 4 ? GV + hl * 128 : RV + (hl - 4) * 128;
;         const bf16_t* vp = proj + (R0 + j) * LD + vcol + vg * 32;
; #pragma unroll
;         for (int q = 0; q < 4; ++q) { const u32x4 w = *(const u32x4*)(vp + q * 8); const int v0 = vg * 32 + q * 8;
;             VT[(v0 + 0) * PT + j] = (bf16_t)(w.x & 0xffff); VT[(v0 + 1) * PT + j] = (bf16_t)(w.x >> 16); VT[(v0 + 2) * PT + j] = (bf16_t)(w.y & 0xffff); VT[(v0 + 3) * PT + j] = (bf16_t)(w.y >> 16);
;             VT[(v0 + 4) * PT + j] = (bf16_t)(w.z & 0xffff); VT[(v0 + 5) * PT + j] = (bf16_t)(w.z >> 16); VT[(v0 + 6) * PT + j] = (bf16_t)(w.w & 0xffff); VT[(v0 + 7) * PT + j] = (bf16_t)(w.w >> 16); } }
.LBB0_172:
	s_or_b64 exec, exec, s[0:1]
	s_and_b32 s15, s13, 63
	s_lshl_b64 s[10:11], s[4:5], 12
	s_lshl_b32 s5, s15, 6
	s_movk_i32 s0, 0xff
	s_or_b32 s10, s10, s5
	v_cmp_lt_i32_e32 vcc, s0, v34
	s_waitcnt lgkmcnt(0)
	s_barrier
	v_lshlrev_b32_e32 v68, 6, v34
	s_lshl_b32 s100, s13, 15
	s_add_u32 s100, s98, s100
	s_addc_u32 s101, s99, 0
	s_add_u32 s100, s100, 0x24300000
	s_addc_u32 s101, s101, 0
	ds_read_b128 v[52:55], v68
	ds_read_b128 v[56:59], v68 offset:16
	ds_read_b128 v[60:63], v68 offset:32
	ds_read_b128 v[64:67], v68 offset:48
	s_waitcnt lgkmcnt(0)
	global_store_dwordx4 v68, v[52:55], s[100:101]
	global_store_dwordx4 v68, v[56:59], s[100:101] offset:16
	global_store_dwordx4 v68, v[60:63], s[100:101] offset:32
	global_store_dwordx4 v68, v[64:67], s[100:101] offset:48
	s_and_saveexec_b64 s[0:1], vcc
	s_xor_b64 s[0:1], exec, s[0:1]
	s_cbranch_execz .LBB0_174
	v_add_u32_e32 v0, 0xffffff00, v34
	v_lshrrev_b32_e32 v0, 2, v0
	s_lshl_b32 s24, s14, 7
	v_lshl_add_u64 v[2:3], s[10:11], 0, v[0:1]
	v_mov_b64_e32 v[4:5], s[22:23]
	s_or_b32 s30, s24, 0xe00
	s_addk_i32 s24, 0x1200
	v_mad_u64_u32 v[4:5], s[28:29], v2, s79, v[4:5]
	s_and_b64 s[28:29], s[8:9], exec
	v_mov_b32_e32 v2, v5
	s_cselect_b32 s24, s30, s24
	v_mad_u64_u32 v[2:3], s[28:29], v3, s79, v[2:3]
	v_mov_b32_e32 v5, v2
	s_lshl_b32 s24, s24, 1
	v_lshl_add_u64 v[2:3], v[4:5], 0, s[24:25]
	v_lshlrev_b32_e32 v4, 5, v34
	v_and_b32_e32 v8, 0x60, v4
	v_lshlrev_b32_e32 v4, 1, v8
	v_mov_b32_e32 v5, v1
	v_lshl_add_u64 v[6:7], v[2:3], 0, v[4:5]
	v_mul_u32_u24_e32 v2, 0x90, v8
	v_lshlrev_b32_e32 v0, 1, v0
	v_add3_u32 v0, 0, v2, v0
	global_load_dwordx4 v[2:5], v[6:7], off
	global_load_dwordx4 v[112:115], v[6:7], off offset:16
	global_load_dwordx4 v[116:119], v[6:7], off offset:32
	global_load_dwordx4 v[120:123], v[6:7], off offset:48
	s_waitcnt vmcnt(0) lgkmcnt(0)
	ds_write_b16 v0, v2 offset:32768
	ds_write_b16_d16_hi v0, v2 offset:32912
	ds_write_b16 v0, v3 offset:33056
	ds_write_b16_d16_hi v0, v3 offset:33200
	ds_write_b16 v0, v4 offset:33344
	ds_write_b16_d16_hi v0, v4 offset:33488
	ds_write_b16 v0, v5 offset:33632
	ds_write_b16_d16_hi v0, v5 offset:33776
	ds_write_b16 v0, v112 offset:33920
	ds_write_b16_d16_hi v0, v112 offset:34064
	ds_write_b16 v0, v113 offset:34208
	ds_write_b16_d16_hi v0, v113 offset:34352
	ds_write_b16 v0, v114 offset:34496
	ds_write_b16_d16_hi v0, v114 offset:34640
	ds_write_b16 v0, v115 offset:34784
	ds_write_b16_d16_hi v0, v115 offset:34928
	ds_write_b16 v0, v116 offset:35072
	ds_write_b16_d16_hi v0, v116 offset:35216
	ds_write_b16 v0, v117 offset:35360
	ds_write_b16_d16_hi v0, v117 offset:35504
	ds_write_b16 v0, v118 offset:35648
	ds_write_b16_d16_hi v0, v118 offset:35792
	ds_write_b16 v0, v119 offset:35936
	ds_write_b16_d16_hi v0, v119 offset:36080
	ds_write_b16 v0, v120 offset:36224
	ds_write_b16_d16_hi v0, v120 offset:36368
	ds_write_b16 v0, v121 offset:36512
	ds_write_b16_d16_hi v0, v121 offset:36656
	ds_write_b16 v0, v122 offset:36800
	ds_write_b16_d16_hi v0, v122 offset:36944
	ds_write_b16 v0, v123 offset:37088
	ds_write_b16_d16_hi v0, v123 offset:37232
